# in-proj K loop: direct HBM->LDS staging (global_load_lds_dwordx4, source-side swizzle) replaces global_load+ds_write_b128; same LDS image and MFMA stream
# speedup vs baseline: 1.0039x; 1.0039x over previous
; template <int EPI>
; DI void gemm_phase(const P& p, int l, const u16* __restrict__ A, const u16* __restrict__ Bt, int mpx, char* lds) {
;     ...
;   {
;   const int lane = tid & 63, w = tid >> 6, r = lane & 15, g = lane >> 4, wm = w >> 2, wn = w & 3;
;   __syncthreads();
;   GLOAD(Ag, Bg, 64)
;   __builtin_amdgcn_sched_barrier(0);
;   GCOMPUTE_KS(As0, Bs0, 0)
;   __builtin_amdgcn_sched_barrier(0);
;   GSTORE(As1, Bs1)
;   GLOAD(Ag, Bg, 128)
;   __builtin_amdgcn_sched_barrier(0);
;   GCOMPUTE_KS(As0, Bs0, 1)
;   __builtin_amdgcn_sched_barrier(0);
.LBB0_81:
	s_mov_b32 s57, s3
	s_lshl_b64 s[42:43], s[56:57], 11
	s_lshl_b32 s2, s51, 11
	s_add_u32 s58, s16, s42
	s_addc_u32 s59, s17, s43
	s_add_u32 s60, s24, s2
	s_addc_u32 s61, s25, 0
	v_lshrrev_b32_e32 v166, 3, v195
	v_and_b32_e32 v167, 7, v195
	v_and_b32_e32 v168, 7, v166
	v_xor_b32_e32 v167, v167, v168
	v_lshlrev_b32_e32 v167, 4, v167
	v_lshl_or_b32 v162, v166, 11, v167
	v_add_u32_e32 v163, s33, v162
	v_add_u32_e32 v164, s35, v162
	v_add_u32_e32 v165, s39, v162
	v_readfirstlane_b32 s47, v195
	s_lshr_b32 s47, s47, 6
	s_lshl_b32 s47, s47, 10
	s_add_u32 s44, s40, 0x80
	s_addc_u32 s45, s41, 0
	s_add_u32 s42, s0, 0x80
	s_addc_u32 s43, s1, 0
	s_mov_b32 s49, 0
	s_waitcnt lgkmcnt(0)
	s_barrier
	ds_read_b128 v[212:215], v204 offset:32768
	ds_read_b128 v[216:219], v204 offset:34816
	ds_read_b128 v[220:223], v204 offset:36864
	ds_read_b128 v[234:237], v204 offset:38912
	ds_read_b128 v[238:241], v205
	ds_read_b128 v[242:245], v205 offset:2048
	ds_read_b128 v[246:249], v205 offset:4096
	ds_read_b128 v[250:253], v205 offset:6144
	s_waitcnt lgkmcnt(3)
	v_mfma_f32_16x16x32_bf16 v[6:9], v[238:241], v[212:215], 0
	v_mfma_f32_16x16x32_bf16 v[10:13], v[238:241], v[216:219], 0
	v_mfma_f32_16x16x32_bf16 v[14:17], v[238:241], v[220:223], 0
	v_mfma_f32_16x16x32_bf16 v[18:21], v[238:241], v[234:237], 0
	ds_read_b128 v[238:241], v205 offset:8192
	s_add_i32 m0, s47, 0x10020
	s_nop 0
	global_load_lds_dwordx4 v162, s[44:45]
	s_add_i32 m0, s47, 0x12020
	s_nop 0
	global_load_lds_dwordx4 v163, s[44:45]
	s_waitcnt lgkmcnt(3)
	v_mfma_f32_16x16x32_bf16 v[22:25], v[242:245], v[212:215], 0
	v_mfma_f32_16x16x32_bf16 v[26:29], v[242:245], v[216:219], 0
	v_mfma_f32_16x16x32_bf16 v[30:33], v[242:245], v[220:223], 0
	v_mfma_f32_16x16x32_bf16 v[34:37], v[242:245], v[234:237], 0
	ds_read_b128 v[242:245], v205 offset:10240
	ds_read_b128 v[130:133], v206 offset:32768
	s_add_i32 m0, s47, 0x14020
	s_nop 0
	global_load_lds_dwordx4 v164, s[44:45]
	s_add_i32 m0, s47, 0x16020
	s_nop 0
	global_load_lds_dwordx4 v165, s[44:45]
	s_waitcnt lgkmcnt(4)
	v_mfma_f32_16x16x32_bf16 v[38:41], v[246:249], v[212:215], 0
	v_mfma_f32_16x16x32_bf16 v[42:45], v[246:249], v[216:219], 0
	v_mfma_f32_16x16x32_bf16 v[46:49], v[246:249], v[220:223], 0
	v_mfma_f32_16x16x32_bf16 v[50:53], v[246:249], v[234:237], 0
	ds_read_b128 v[246:249], v205 offset:12288
	ds_read_b128 v[134:137], v206 offset:34816
	s_add_i32 m0, s47, 0x18020
	s_nop 0
	global_load_lds_dwordx4 v162, s[42:43]
	s_add_i32 m0, s47, 0x1a020
	s_nop 0
	global_load_lds_dwordx4 v163, s[42:43]
	s_waitcnt lgkmcnt(5)
	v_mfma_f32_16x16x32_bf16 v[54:57], v[250:253], v[212:215], 0
	v_mfma_f32_16x16x32_bf16 v[58:61], v[250:253], v[216:219], 0
	v_mfma_f32_16x16x32_bf16 v[62:65], v[250:253], v[220:223], 0
	v_mfma_f32_16x16x32_bf16 v[66:69], v[250:253], v[234:237], 0
	ds_read_b128 v[250:253], v205 offset:14336
	ds_read_b128 v[138:141], v206 offset:36864
	s_add_i32 m0, s47, 0x1c020
	s_nop 0
	global_load_lds_dwordx4 v164, s[42:43]
	s_add_i32 m0, s47, 0x1e020
	s_nop 0
	global_load_lds_dwordx4 v165, s[42:43]
	s_waitcnt lgkmcnt(6)
	v_mfma_f32_16x16x32_bf16 v[70:73], v[238:241], v[212:215], 0
	v_mfma_f32_16x16x32_bf16 v[74:77], v[238:241], v[216:219], 0
	v_mfma_f32_16x16x32_bf16 v[78:81], v[238:241], v[220:223], 0
	v_mfma_f32_16x16x32_bf16 v[82:85], v[238:241], v[234:237], 0
	ds_read_b128 v[238:241], v207
	ds_read_b128 v[142:145], v206 offset:38912
	s_waitcnt lgkmcnt(7)
	v_mfma_f32_16x16x32_bf16 v[86:89], v[242:245], v[212:215], 0
	v_mfma_f32_16x16x32_bf16 v[90:93], v[242:245], v[216:219], 0
	v_mfma_f32_16x16x32_bf16 v[94:97], v[242:245], v[220:223], 0
	v_mfma_f32_16x16x32_bf16 v[98:101], v[242:245], v[234:237], 0
	ds_read_b128 v[242:245], v207 offset:2048
	s_waitcnt lgkmcnt(6)
	v_mfma_f32_16x16x32_bf16 v[102:105], v[246:249], v[212:215], 0
	v_mfma_f32_16x16x32_bf16 v[106:109], v[246:249], v[216:219], 0
	v_mfma_f32_16x16x32_bf16 v[110:113], v[246:249], v[220:223], 0
	v_mfma_f32_16x16x32_bf16 v[114:117], v[246:249], v[234:237], 0
	ds_read_b128 v[246:249], v207 offset:4096
	s_waitcnt lgkmcnt(5)
	v_mfma_f32_16x16x32_bf16 v[118:121], v[250:253], v[212:215], 0
	v_mfma_f32_16x16x32_bf16 v[122:125], v[250:253], v[216:219], 0
	v_mfma_f32_16x16x32_bf16 v[126:129], v[250:253], v[220:223], 0
	v_mfma_f32_16x16x32_bf16 v[2:5], v[250:253], v[234:237], 0
	ds_read_b128 v[250:253], v207 offset:6144
	s_waitcnt lgkmcnt(3)
	v_mfma_f32_16x16x32_bf16 v[6:9], v[238:241], v[130:133], v[6:9]
	v_mfma_f32_16x16x32_bf16 v[10:13], v[238:241], v[134:137], v[10:13]
	v_mfma_f32_16x16x32_bf16 v[14:17], v[238:241], v[138:141], v[14:17]
	v_mfma_f32_16x16x32_bf16 v[18:21], v[238:241], v[142:145], v[18:21]
	ds_read_b128 v[238:241], v207 offset:8192
	s_waitcnt lgkmcnt(3)
	v_mfma_f32_16x16x32_bf16 v[22:25], v[242:245], v[130:133], v[22:25]
	v_mfma_f32_16x16x32_bf16 v[26:29], v[242:245], v[134:137], v[26:29]
	v_mfma_f32_16x16x32_bf16 v[30:33], v[242:245], v[138:141], v[30:33]
	v_mfma_f32_16x16x32_bf16 v[34:37], v[242:245], v[142:145], v[34:37]
	ds_read_b128 v[242:245], v207 offset:10240
	s_waitcnt lgkmcnt(3)
	v_mfma_f32_16x16x32_bf16 v[38:41], v[246:249], v[130:133], v[38:41]
	v_mfma_f32_16x16x32_bf16 v[42:45], v[246:249], v[134:137], v[42:45]
	v_mfma_f32_16x16x32_bf16 v[46:49], v[246:249], v[138:141], v[46:49]
	v_mfma_f32_16x16x32_bf16 v[50:53], v[246:249], v[142:145], v[50:53]
	ds_read_b128 v[246:249], v207 offset:12288
	s_waitcnt lgkmcnt(3)
	v_mfma_f32_16x16x32_bf16 v[54:57], v[250:253], v[130:133], v[54:57]
	v_mfma_f32_16x16x32_bf16 v[58:61], v[250:253], v[134:137], v[58:61]
	v_mfma_f32_16x16x32_bf16 v[62:65], v[250:253], v[138:141], v[62:65]
	v_mfma_f32_16x16x32_bf16 v[66:69], v[250:253], v[142:145], v[66:69]
	ds_read_b128 v[250:253], v207 offset:14336
	s_waitcnt lgkmcnt(3)
	v_mfma_f32_16x16x32_bf16 v[70:73], v[238:241], v[130:133], v[70:73]
	v_mfma_f32_16x16x32_bf16 v[74:77], v[238:241], v[134:137], v[74:77]
	v_mfma_f32_16x16x32_bf16 v[78:81], v[238:241], v[138:141], v[78:81]
	v_mfma_f32_16x16x32_bf16 v[82:85], v[238:241], v[142:145], v[82:85]
	s_waitcnt lgkmcnt(2)
	v_mfma_f32_16x16x32_bf16 v[86:89], v[242:245], v[130:133], v[86:89]
	v_mfma_f32_16x16x32_bf16 v[90:93], v[242:245], v[134:137], v[90:93]
	v_mfma_f32_16x16x32_bf16 v[94:97], v[242:245], v[138:141], v[94:97]
	v_mfma_f32_16x16x32_bf16 v[98:101], v[242:245], v[142:145], v[98:101]
	s_waitcnt lgkmcnt(0)
	s_waitcnt vmcnt(0)
	s_add_u32 s44, s44, 0x80
	s_addc_u32 s45, s45, 0
	s_add_u32 s42, s42, 0x80
	s_addc_u32 s43, s43, 0
	s_barrier
; #define GCOMPUTE(AS, BS) GCOMPUTE_KS(AS, BS, 0) GCOMPUTE_KS(AS, BS, 1)
; template <int EPI>
; DI void gemm_phase(const P& p, int l, const u16* __restrict__ A, const u16* __restrict__ Bt, int mpx, char* lds) {
;     ...
;   for (int kk = 1; kk < 15; kk += 2) {
;     __syncthreads();
;     GSTORE(As0, Bs0)
;     GLOAD(Ag, Bg, (kk + 2) * 64)
;     __builtin_amdgcn_sched_barrier(0);
;     GCOMPUTE(As1, Bs1)
;     __builtin_amdgcn_sched_barrier(0);
;     __syncthreads();
;     GSTORE(As1, Bs1)
;     {
;       const bool in_tile = kk + 3 < 16;
;       const u16* pa = in_tile ? Ag : Agn;
;       const u16* pb = in_tile ? Bg : Bgn;
;       const int k0 = in_tile ? (kk + 3) * 64 : 0;
;       GLOAD(pa, pb, k0)
;     }
;     __builtin_amdgcn_sched_barrier(0);
;     GCOMPUTE(As0, Bs0)
;     __builtin_amdgcn_sched_barrier(0);
	ds_read_b128 v[212:215], v198
	ds_read_b128 v[216:219], v198 offset:2048
	ds_read_b128 v[220:223], v198 offset:4096
	ds_read_b128 v[234:237], v198 offset:6144
	ds_read_b128 v[238:241], v199
	ds_read_b128 v[242:245], v199 offset:2048
	v_mfma_f32_16x16x32_bf16 v[102:105], v[246:249], v[130:133], v[102:105]
	v_mfma_f32_16x16x32_bf16 v[106:109], v[246:249], v[134:137], v[106:109]
	v_mfma_f32_16x16x32_bf16 v[110:113], v[246:249], v[138:141], v[110:113]
	v_mfma_f32_16x16x32_bf16 v[114:117], v[246:249], v[142:145], v[114:117]
	ds_read_b128 v[246:249], v199 offset:4096
	v_mfma_f32_16x16x32_bf16 v[118:121], v[250:253], v[130:133], v[118:121]
	v_mfma_f32_16x16x32_bf16 v[122:125], v[250:253], v[134:137], v[122:125]
	v_mfma_f32_16x16x32_bf16 v[126:129], v[250:253], v[138:141], v[126:129]
	v_mfma_f32_16x16x32_bf16 v[2:5], v[250:253], v[142:145], v[2:5]
	ds_read_b128 v[250:253], v199 offset:6144
.LBB0_82:
	s_waitcnt lgkmcnt(3)
	v_mfma_f32_16x16x32_bf16 v[6:9], v[238:241], v[212:215], v[6:9]
	v_mfma_f32_16x16x32_bf16 v[10:13], v[238:241], v[216:219], v[10:13]
	v_mfma_f32_16x16x32_bf16 v[14:17], v[238:241], v[220:223], v[14:17]
	v_mfma_f32_16x16x32_bf16 v[18:21], v[238:241], v[234:237], v[18:21]
	ds_read_b128 v[238:241], v199 offset:8192
	s_add_i32 m0, s47, 0x20
	s_nop 0
	global_load_lds_dwordx4 v162, s[44:45]
	s_add_i32 m0, s47, 0x2020
	s_nop 0
	global_load_lds_dwordx4 v163, s[44:45]
	s_waitcnt lgkmcnt(3)
	v_mfma_f32_16x16x32_bf16 v[22:25], v[242:245], v[212:215], v[22:25]
	v_mfma_f32_16x16x32_bf16 v[26:29], v[242:245], v[216:219], v[26:29]
	v_mfma_f32_16x16x32_bf16 v[30:33], v[242:245], v[220:223], v[30:33]
	v_mfma_f32_16x16x32_bf16 v[34:37], v[242:245], v[234:237], v[34:37]
	ds_read_b128 v[242:245], v199 offset:10240
	ds_read_b128 v[130:133], v200
	s_add_i32 m0, s47, 0x4020
	s_nop 0
	global_load_lds_dwordx4 v164, s[44:45]
	s_add_i32 m0, s47, 0x6020
	s_nop 0
	global_load_lds_dwordx4 v165, s[44:45]
	s_waitcnt lgkmcnt(4)
	v_mfma_f32_16x16x32_bf16 v[38:41], v[246:249], v[212:215], v[38:41]
	v_mfma_f32_16x16x32_bf16 v[42:45], v[246:249], v[216:219], v[42:45]
	v_mfma_f32_16x16x32_bf16 v[46:49], v[246:249], v[220:223], v[46:49]
	v_mfma_f32_16x16x32_bf16 v[50:53], v[246:249], v[234:237], v[50:53]
	ds_read_b128 v[246:249], v199 offset:12288
	ds_read_b128 v[134:137], v200 offset:2048
	s_add_i32 m0, s47, 0x8020
	s_nop 0
	global_load_lds_dwordx4 v162, s[42:43]
	s_add_i32 m0, s47, 0xa020
	s_nop 0
	global_load_lds_dwordx4 v163, s[42:43]
	s_waitcnt lgkmcnt(5)
	v_mfma_f32_16x16x32_bf16 v[54:57], v[250:253], v[212:215], v[54:57]
	v_mfma_f32_16x16x32_bf16 v[58:61], v[250:253], v[216:219], v[58:61]
	v_mfma_f32_16x16x32_bf16 v[62:65], v[250:253], v[220:223], v[62:65]
	v_mfma_f32_16x16x32_bf16 v[66:69], v[250:253], v[234:237], v[66:69]
	ds_read_b128 v[250:253], v199 offset:14336
	ds_read_b128 v[138:141], v200 offset:4096
	s_add_i32 m0, s47, 0xc020
	s_nop 0
	global_load_lds_dwordx4 v164, s[42:43]
	s_add_i32 m0, s47, 0xe020
	s_nop 0
	global_load_lds_dwordx4 v165, s[42:43]
	s_waitcnt lgkmcnt(6)
	v_mfma_f32_16x16x32_bf16 v[70:73], v[238:241], v[212:215], v[70:73]
	v_mfma_f32_16x16x32_bf16 v[74:77], v[238:241], v[216:219], v[74:77]
	v_mfma_f32_16x16x32_bf16 v[78:81], v[238:241], v[220:223], v[78:81]
	v_mfma_f32_16x16x32_bf16 v[82:85], v[238:241], v[234:237], v[82:85]
	ds_read_b128 v[238:241], v233
	ds_read_b128 v[142:145], v200 offset:6144
	s_waitcnt lgkmcnt(7)
	v_mfma_f32_16x16x32_bf16 v[86:89], v[242:245], v[212:215], v[86:89]
	v_mfma_f32_16x16x32_bf16 v[90:93], v[242:245], v[216:219], v[90:93]
	v_mfma_f32_16x16x32_bf16 v[94:97], v[242:245], v[220:223], v[94:97]
	v_mfma_f32_16x16x32_bf16 v[98:101], v[242:245], v[234:237], v[98:101]
	ds_read_b128 v[242:245], v233 offset:2048
	s_waitcnt lgkmcnt(6)
	v_mfma_f32_16x16x32_bf16 v[102:105], v[246:249], v[212:215], v[102:105]
	v_mfma_f32_16x16x32_bf16 v[106:109], v[246:249], v[216:219], v[106:109]
	v_mfma_f32_16x16x32_bf16 v[110:113], v[246:249], v[220:223], v[110:113]
	v_mfma_f32_16x16x32_bf16 v[114:117], v[246:249], v[234:237], v[114:117]
	ds_read_b128 v[246:249], v233 offset:4096
	s_waitcnt lgkmcnt(5)
	v_mfma_f32_16x16x32_bf16 v[118:121], v[250:253], v[212:215], v[118:121]
	v_mfma_f32_16x16x32_bf16 v[122:125], v[250:253], v[216:219], v[122:125]
	v_mfma_f32_16x16x32_bf16 v[126:129], v[250:253], v[220:223], v[126:129]
	v_mfma_f32_16x16x32_bf16 v[2:5], v[250:253], v[234:237], v[2:5]
	ds_read_b128 v[250:253], v233 offset:6144
	s_waitcnt lgkmcnt(3)
	v_mfma_f32_16x16x32_bf16 v[6:9], v[238:241], v[130:133], v[6:9]
	v_mfma_f32_16x16x32_bf16 v[10:13], v[238:241], v[134:137], v[10:13]
	v_mfma_f32_16x16x32_bf16 v[14:17], v[238:241], v[138:141], v[14:17]
	v_mfma_f32_16x16x32_bf16 v[18:21], v[238:241], v[142:145], v[18:21]
	ds_read_b128 v[238:241], v233 offset:8192
	s_waitcnt lgkmcnt(3)
	v_mfma_f32_16x16x32_bf16 v[22:25], v[242:245], v[130:133], v[22:25]
	v_mfma_f32_16x16x32_bf16 v[26:29], v[242:245], v[134:137], v[26:29]
	v_mfma_f32_16x16x32_bf16 v[30:33], v[242:245], v[138:141], v[30:33]
	v_mfma_f32_16x16x32_bf16 v[34:37], v[242:245], v[142:145], v[34:37]
	ds_read_b128 v[242:245], v233 offset:10240
	s_waitcnt lgkmcnt(3)
	v_mfma_f32_16x16x32_bf16 v[38:41], v[246:249], v[130:133], v[38:41]
	v_mfma_f32_16x16x32_bf16 v[42:45], v[246:249], v[134:137], v[42:45]
	v_mfma_f32_16x16x32_bf16 v[46:49], v[246:249], v[138:141], v[46:49]
	v_mfma_f32_16x16x32_bf16 v[50:53], v[246:249], v[142:145], v[50:53]
	ds_read_b128 v[246:249], v233 offset:12288
	s_waitcnt lgkmcnt(3)
	v_mfma_f32_16x16x32_bf16 v[54:57], v[250:253], v[130:133], v[54:57]
	v_mfma_f32_16x16x32_bf16 v[58:61], v[250:253], v[134:137], v[58:61]
	v_mfma_f32_16x16x32_bf16 v[62:65], v[250:253], v[138:141], v[62:65]
	v_mfma_f32_16x16x32_bf16 v[66:69], v[250:253], v[142:145], v[66:69]
	ds_read_b128 v[250:253], v233 offset:14336
	s_waitcnt lgkmcnt(3)
	v_mfma_f32_16x16x32_bf16 v[70:73], v[238:241], v[130:133], v[70:73]
	v_mfma_f32_16x16x32_bf16 v[74:77], v[238:241], v[134:137], v[74:77]
	v_mfma_f32_16x16x32_bf16 v[78:81], v[238:241], v[138:141], v[78:81]
	v_mfma_f32_16x16x32_bf16 v[82:85], v[238:241], v[142:145], v[82:85]
	s_waitcnt lgkmcnt(2)
	v_mfma_f32_16x16x32_bf16 v[86:89], v[242:245], v[130:133], v[86:89]
	v_mfma_f32_16x16x32_bf16 v[90:93], v[242:245], v[134:137], v[90:93]
	v_mfma_f32_16x16x32_bf16 v[94:97], v[242:245], v[138:141], v[94:97]
	v_mfma_f32_16x16x32_bf16 v[98:101], v[242:245], v[142:145], v[98:101]
	s_waitcnt lgkmcnt(0)
	s_waitcnt vmcnt(0)
	s_add_u32 s44, s44, 0x80
	s_addc_u32 s45, s45, 0
	s_add_u32 s42, s42, 0x80
	s_addc_u32 s43, s43, 0
	s_barrier
; #define GCOMPUTE(AS, BS) GCOMPUTE_KS(AS, BS, 0) GCOMPUTE_KS(AS, BS, 1)
; template <int EPI>
; DI void gemm_phase(const P& p, int l, const u16* __restrict__ A, const u16* __restrict__ Bt, int mpx, char* lds) {
;     ...
;     __syncthreads();
;     GSTORE(As1, Bs1)
;     {
;       const bool in_tile = kk + 3 < 16;
;       const u16* pa = in_tile ? Ag : Agn;
;       const u16* pb = in_tile ? Bg : Bgn;
;       const int k0 = in_tile ? (kk + 3) * 64 : 0;
;       GLOAD(pa, pb, k0)
;     }
;     __builtin_amdgcn_sched_barrier(0);
;     GCOMPUTE(As0, Bs0)
;     __builtin_amdgcn_sched_barrier(0);
;   }
	ds_read_b128 v[212:215], v204 offset:32768
	ds_read_b128 v[216:219], v204 offset:34816
	ds_read_b128 v[220:223], v204 offset:36864
	ds_read_b128 v[234:237], v204 offset:38912
	ds_read_b128 v[238:241], v205
	ds_read_b128 v[242:245], v205 offset:2048
	v_mfma_f32_16x16x32_bf16 v[102:105], v[246:249], v[130:133], v[102:105]
	v_mfma_f32_16x16x32_bf16 v[106:109], v[246:249], v[134:137], v[106:109]
	v_mfma_f32_16x16x32_bf16 v[110:113], v[246:249], v[138:141], v[110:113]
	v_mfma_f32_16x16x32_bf16 v[114:117], v[246:249], v[142:145], v[114:117]
	ds_read_b128 v[246:249], v205 offset:4096
	v_mfma_f32_16x16x32_bf16 v[118:121], v[250:253], v[130:133], v[118:121]
	v_mfma_f32_16x16x32_bf16 v[122:125], v[250:253], v[134:137], v[122:125]
	v_mfma_f32_16x16x32_bf16 v[126:129], v[250:253], v[138:141], v[126:129]
	v_mfma_f32_16x16x32_bf16 v[2:5], v[250:253], v[142:145], v[2:5]
	ds_read_b128 v[250:253], v205 offset:6144
	s_waitcnt lgkmcnt(3)
	v_mfma_f32_16x16x32_bf16 v[6:9], v[238:241], v[212:215], v[6:9]
	v_mfma_f32_16x16x32_bf16 v[10:13], v[238:241], v[216:219], v[10:13]
	v_mfma_f32_16x16x32_bf16 v[14:17], v[238:241], v[220:223], v[14:17]
	v_mfma_f32_16x16x32_bf16 v[18:21], v[238:241], v[234:237], v[18:21]
	ds_read_b128 v[238:241], v205 offset:8192
	s_add_i32 m0, s47, 0x10020
	s_nop 0
	global_load_lds_dwordx4 v162, s[44:45]
	s_add_i32 m0, s47, 0x12020
	s_nop 0
	global_load_lds_dwordx4 v163, s[44:45]
	s_waitcnt lgkmcnt(3)
	v_mfma_f32_16x16x32_bf16 v[22:25], v[242:245], v[212:215], v[22:25]
	v_mfma_f32_16x16x32_bf16 v[26:29], v[242:245], v[216:219], v[26:29]
	v_mfma_f32_16x16x32_bf16 v[30:33], v[242:245], v[220:223], v[30:33]
	v_mfma_f32_16x16x32_bf16 v[34:37], v[242:245], v[234:237], v[34:37]
	ds_read_b128 v[242:245], v205 offset:10240
	ds_read_b128 v[130:133], v206 offset:32768
	s_add_i32 m0, s47, 0x14020
	s_nop 0
	global_load_lds_dwordx4 v164, s[44:45]
	s_add_i32 m0, s47, 0x16020
	s_nop 0
	global_load_lds_dwordx4 v165, s[44:45]
	s_waitcnt lgkmcnt(4)
	v_mfma_f32_16x16x32_bf16 v[38:41], v[246:249], v[212:215], v[38:41]
	v_mfma_f32_16x16x32_bf16 v[42:45], v[246:249], v[216:219], v[42:45]
	v_mfma_f32_16x16x32_bf16 v[46:49], v[246:249], v[220:223], v[46:49]
	v_mfma_f32_16x16x32_bf16 v[50:53], v[246:249], v[234:237], v[50:53]
	ds_read_b128 v[246:249], v205 offset:12288
	ds_read_b128 v[134:137], v206 offset:34816
	s_add_i32 m0, s47, 0x18020
	s_nop 0
	global_load_lds_dwordx4 v162, s[42:43]
	s_add_i32 m0, s47, 0x1a020
	s_nop 0
	global_load_lds_dwordx4 v163, s[42:43]
	s_waitcnt lgkmcnt(5)
	v_mfma_f32_16x16x32_bf16 v[54:57], v[250:253], v[212:215], v[54:57]
	v_mfma_f32_16x16x32_bf16 v[58:61], v[250:253], v[216:219], v[58:61]
	v_mfma_f32_16x16x32_bf16 v[62:65], v[250:253], v[220:223], v[62:65]
	v_mfma_f32_16x16x32_bf16 v[66:69], v[250:253], v[234:237], v[66:69]
	ds_read_b128 v[250:253], v205 offset:14336
	ds_read_b128 v[138:141], v206 offset:36864
	s_add_i32 m0, s47, 0x1c020
	s_nop 0
	global_load_lds_dwordx4 v164, s[42:43]
	s_add_i32 m0, s47, 0x1e020
	s_nop 0
	global_load_lds_dwordx4 v165, s[42:43]
	s_waitcnt lgkmcnt(6)
	v_mfma_f32_16x16x32_bf16 v[70:73], v[238:241], v[212:215], v[70:73]
	v_mfma_f32_16x16x32_bf16 v[74:77], v[238:241], v[216:219], v[74:77]
	v_mfma_f32_16x16x32_bf16 v[78:81], v[238:241], v[220:223], v[78:81]
	v_mfma_f32_16x16x32_bf16 v[82:85], v[238:241], v[234:237], v[82:85]
	ds_read_b128 v[238:241], v207
	ds_read_b128 v[142:145], v206 offset:38912
	s_waitcnt lgkmcnt(7)
	v_mfma_f32_16x16x32_bf16 v[86:89], v[242:245], v[212:215], v[86:89]
	v_mfma_f32_16x16x32_bf16 v[90:93], v[242:245], v[216:219], v[90:93]
	v_mfma_f32_16x16x32_bf16 v[94:97], v[242:245], v[220:223], v[94:97]
	v_mfma_f32_16x16x32_bf16 v[98:101], v[242:245], v[234:237], v[98:101]
	ds_read_b128 v[242:245], v207 offset:2048
	s_waitcnt lgkmcnt(6)
	v_mfma_f32_16x16x32_bf16 v[102:105], v[246:249], v[212:215], v[102:105]
	v_mfma_f32_16x16x32_bf16 v[106:109], v[246:249], v[216:219], v[106:109]
	v_mfma_f32_16x16x32_bf16 v[110:113], v[246:249], v[220:223], v[110:113]
	v_mfma_f32_16x16x32_bf16 v[114:117], v[246:249], v[234:237], v[114:117]
	ds_read_b128 v[246:249], v207 offset:4096
	s_waitcnt lgkmcnt(5)
	v_mfma_f32_16x16x32_bf16 v[118:121], v[250:253], v[212:215], v[118:121]
	v_mfma_f32_16x16x32_bf16 v[122:125], v[250:253], v[216:219], v[122:125]
	v_mfma_f32_16x16x32_bf16 v[126:129], v[250:253], v[220:223], v[126:129]
	v_mfma_f32_16x16x32_bf16 v[2:5], v[250:253], v[234:237], v[2:5]
	ds_read_b128 v[250:253], v207 offset:6144
	s_waitcnt lgkmcnt(3)
	v_mfma_f32_16x16x32_bf16 v[6:9], v[238:241], v[130:133], v[6:9]
	v_mfma_f32_16x16x32_bf16 v[10:13], v[238:241], v[134:137], v[10:13]
	v_mfma_f32_16x16x32_bf16 v[14:17], v[238:241], v[138:141], v[14:17]
	v_mfma_f32_16x16x32_bf16 v[18:21], v[238:241], v[142:145], v[18:21]
	ds_read_b128 v[238:241], v207 offset:8192
	s_waitcnt lgkmcnt(3)
	v_mfma_f32_16x16x32_bf16 v[22:25], v[242:245], v[130:133], v[22:25]
	v_mfma_f32_16x16x32_bf16 v[26:29], v[242:245], v[134:137], v[26:29]
	v_mfma_f32_16x16x32_bf16 v[30:33], v[242:245], v[138:141], v[30:33]
	v_mfma_f32_16x16x32_bf16 v[34:37], v[242:245], v[142:145], v[34:37]
	ds_read_b128 v[242:245], v207 offset:10240
	s_waitcnt lgkmcnt(3)
	v_mfma_f32_16x16x32_bf16 v[38:41], v[246:249], v[130:133], v[38:41]
	v_mfma_f32_16x16x32_bf16 v[42:45], v[246:249], v[134:137], v[42:45]
	v_mfma_f32_16x16x32_bf16 v[46:49], v[246:249], v[138:141], v[46:49]
	v_mfma_f32_16x16x32_bf16 v[50:53], v[246:249], v[142:145], v[50:53]
	ds_read_b128 v[246:249], v207 offset:12288
	s_waitcnt lgkmcnt(3)
	v_mfma_f32_16x16x32_bf16 v[54:57], v[250:253], v[130:133], v[54:57]
	v_mfma_f32_16x16x32_bf16 v[58:61], v[250:253], v[134:137], v[58:61]
	v_mfma_f32_16x16x32_bf16 v[62:65], v[250:253], v[138:141], v[62:65]
	v_mfma_f32_16x16x32_bf16 v[66:69], v[250:253], v[142:145], v[66:69]
	ds_read_b128 v[250:253], v207 offset:14336
	s_waitcnt lgkmcnt(3)
	v_mfma_f32_16x16x32_bf16 v[70:73], v[238:241], v[130:133], v[70:73]
	v_mfma_f32_16x16x32_bf16 v[74:77], v[238:241], v[134:137], v[74:77]
	v_mfma_f32_16x16x32_bf16 v[78:81], v[238:241], v[138:141], v[78:81]
	v_mfma_f32_16x16x32_bf16 v[82:85], v[238:241], v[142:145], v[82:85]
	s_waitcnt lgkmcnt(2)
	v_mfma_f32_16x16x32_bf16 v[86:89], v[242:245], v[130:133], v[86:89]
	v_mfma_f32_16x16x32_bf16 v[90:93], v[242:245], v[134:137], v[90:93]
	v_mfma_f32_16x16x32_bf16 v[94:97], v[242:245], v[138:141], v[94:97]
	v_mfma_f32_16x16x32_bf16 v[98:101], v[242:245], v[142:145], v[98:101]
	s_waitcnt lgkmcnt(0)
	s_waitcnt vmcnt(0)
	s_add_u32 s44, s44, 0x80
	s_addc_u32 s45, s45, 0
	s_add_u32 s42, s42, 0x80
	s_addc_u32 s43, s43, 0
	s_add_i32 s49, s49, 1
	s_cmp_lt_u32 s49, 7
	s_barrier
; #define GCOMPUTE(AS, BS) GCOMPUTE_KS(AS, BS, 0) GCOMPUTE_KS(AS, BS, 1)
; template <int EPI>
; DI void gemm_phase(const P& p, int l, const u16* __restrict__ A, const u16* __restrict__ Bt, int mpx, char* lds) {
;     ...
;     __syncthreads();
;     GSTORE(As1, Bs1)
;     {
;       const bool in_tile = kk + 3 < 16;
;       const u16* pa = in_tile ? Ag : Agn;
;       const u16* pb = in_tile ? Bg : Bgn;
;       const int k0 = in_tile ? (kk + 3) * 64 : 0;
;       GLOAD(pa, pb, k0)
;     }
;     __builtin_amdgcn_sched_barrier(0);
;     GCOMPUTE(As0, Bs0)
;     __builtin_amdgcn_sched_barrier(0);
;   }
;   __syncthreads();
;   __builtin_amdgcn_sched_barrier(0);
;   GCOMPUTE(As1, Bs1)
;   __builtin_amdgcn_sched_barrier(0);
;   }
;   __syncthreads();
;   GSTORE(As0, Bs0)
	ds_read_b128 v[212:215], v198
	ds_read_b128 v[216:219], v198 offset:2048
	ds_read_b128 v[220:223], v198 offset:4096
	ds_read_b128 v[234:237], v198 offset:6144
	ds_read_b128 v[238:241], v199
	ds_read_b128 v[242:245], v199 offset:2048
	v_mfma_f32_16x16x32_bf16 v[102:105], v[246:249], v[130:133], v[102:105]
	v_mfma_f32_16x16x32_bf16 v[106:109], v[246:249], v[134:137], v[106:109]
	v_mfma_f32_16x16x32_bf16 v[110:113], v[246:249], v[138:141], v[110:113]
	v_mfma_f32_16x16x32_bf16 v[114:117], v[246:249], v[142:145], v[114:117]
	ds_read_b128 v[246:249], v199 offset:4096
	v_mfma_f32_16x16x32_bf16 v[118:121], v[250:253], v[130:133], v[118:121]
	v_mfma_f32_16x16x32_bf16 v[122:125], v[250:253], v[134:137], v[122:125]
	v_mfma_f32_16x16x32_bf16 v[126:129], v[250:253], v[138:141], v[126:129]
	v_mfma_f32_16x16x32_bf16 v[2:5], v[250:253], v[142:145], v[2:5]
	ds_read_b128 v[250:253], v199 offset:6144
	s_cbranch_scc1 .LBB0_82
	s_waitcnt lgkmcnt(3)
	v_mfma_f32_16x16x32_bf16 v[6:9], v[238:241], v[212:215], v[6:9]
	v_mfma_f32_16x16x32_bf16 v[10:13], v[238:241], v[216:219], v[10:13]
	v_mfma_f32_16x16x32_bf16 v[14:17], v[238:241], v[220:223], v[14:17]
	v_mfma_f32_16x16x32_bf16 v[18:21], v[238:241], v[234:237], v[18:21]
	ds_read_b128 v[238:241], v199 offset:8192
	s_add_i32 m0, s47, 0x20
	s_nop 0
	global_load_lds_dwordx4 v162, s[58:59]
	s_add_i32 m0, s47, 0x2020
	s_nop 0
	global_load_lds_dwordx4 v163, s[58:59]
	s_waitcnt lgkmcnt(3)
	v_mfma_f32_16x16x32_bf16 v[22:25], v[242:245], v[212:215], v[22:25]
	v_mfma_f32_16x16x32_bf16 v[26:29], v[242:245], v[216:219], v[26:29]
	v_mfma_f32_16x16x32_bf16 v[30:33], v[242:245], v[220:223], v[30:33]
	v_mfma_f32_16x16x32_bf16 v[34:37], v[242:245], v[234:237], v[34:37]
	ds_read_b128 v[242:245], v199 offset:10240
	ds_read_b128 v[130:133], v200
	s_add_i32 m0, s47, 0x4020
	s_nop 0
	global_load_lds_dwordx4 v164, s[58:59]
	s_add_i32 m0, s47, 0x6020
	s_nop 0
	global_load_lds_dwordx4 v165, s[58:59]
	s_waitcnt lgkmcnt(4)
	v_mfma_f32_16x16x32_bf16 v[38:41], v[246:249], v[212:215], v[38:41]
	v_mfma_f32_16x16x32_bf16 v[42:45], v[246:249], v[216:219], v[42:45]
	v_mfma_f32_16x16x32_bf16 v[46:49], v[246:249], v[220:223], v[46:49]
	v_mfma_f32_16x16x32_bf16 v[50:53], v[246:249], v[234:237], v[50:53]
	ds_read_b128 v[246:249], v199 offset:12288
	ds_read_b128 v[134:137], v200 offset:2048
	s_add_i32 m0, s47, 0x8020
	s_nop 0
	global_load_lds_dwordx4 v162, s[60:61]
	s_add_i32 m0, s47, 0xa020
	s_nop 0
	global_load_lds_dwordx4 v163, s[60:61]
	s_waitcnt lgkmcnt(5)
	v_mfma_f32_16x16x32_bf16 v[54:57], v[250:253], v[212:215], v[54:57]
	v_mfma_f32_16x16x32_bf16 v[58:61], v[250:253], v[216:219], v[58:61]
	v_mfma_f32_16x16x32_bf16 v[62:65], v[250:253], v[220:223], v[62:65]
	v_mfma_f32_16x16x32_bf16 v[66:69], v[250:253], v[234:237], v[66:69]
	ds_read_b128 v[250:253], v199 offset:14336
	ds_read_b128 v[138:141], v200 offset:4096
	s_add_i32 m0, s47, 0xc020
	s_nop 0
	global_load_lds_dwordx4 v164, s[60:61]
	s_add_i32 m0, s47, 0xe020
	s_nop 0
	global_load_lds_dwordx4 v165, s[60:61]
	s_waitcnt lgkmcnt(6)
	v_mfma_f32_16x16x32_bf16 v[70:73], v[238:241], v[212:215], v[70:73]
	v_mfma_f32_16x16x32_bf16 v[74:77], v[238:241], v[216:219], v[74:77]
	v_mfma_f32_16x16x32_bf16 v[78:81], v[238:241], v[220:223], v[78:81]
	v_mfma_f32_16x16x32_bf16 v[82:85], v[238:241], v[234:237], v[82:85]
	ds_read_b128 v[238:241], v233
	ds_read_b128 v[142:145], v200 offset:6144
	s_waitcnt lgkmcnt(7)
	v_mfma_f32_16x16x32_bf16 v[86:89], v[242:245], v[212:215], v[86:89]
	v_mfma_f32_16x16x32_bf16 v[90:93], v[242:245], v[216:219], v[90:93]
	v_mfma_f32_16x16x32_bf16 v[94:97], v[242:245], v[220:223], v[94:97]
	v_mfma_f32_16x16x32_bf16 v[98:101], v[242:245], v[234:237], v[98:101]
	ds_read_b128 v[242:245], v233 offset:2048
	s_waitcnt lgkmcnt(6)
	v_mfma_f32_16x16x32_bf16 v[102:105], v[246:249], v[212:215], v[102:105]
	v_mfma_f32_16x16x32_bf16 v[106:109], v[246:249], v[216:219], v[106:109]
	v_mfma_f32_16x16x32_bf16 v[110:113], v[246:249], v[220:223], v[110:113]
	v_mfma_f32_16x16x32_bf16 v[114:117], v[246:249], v[234:237], v[114:117]
	ds_read_b128 v[246:249], v233 offset:4096
	s_waitcnt lgkmcnt(5)
	v_mfma_f32_16x16x32_bf16 v[118:121], v[250:253], v[212:215], v[118:121]
	v_mfma_f32_16x16x32_bf16 v[122:125], v[250:253], v[216:219], v[122:125]
	v_mfma_f32_16x16x32_bf16 v[126:129], v[250:253], v[220:223], v[126:129]
	v_mfma_f32_16x16x32_bf16 v[2:5], v[250:253], v[234:237], v[2:5]
	ds_read_b128 v[250:253], v233 offset:6144
	s_waitcnt lgkmcnt(3)
	v_mfma_f32_16x16x32_bf16 v[6:9], v[238:241], v[130:133], v[6:9]
	v_mfma_f32_16x16x32_bf16 v[10:13], v[238:241], v[134:137], v[10:13]
	v_mfma_f32_16x16x32_bf16 v[14:17], v[238:241], v[138:141], v[14:17]
	v_mfma_f32_16x16x32_bf16 v[18:21], v[238:241], v[142:145], v[18:21]
	ds_read_b128 v[238:241], v233 offset:8192
	s_waitcnt lgkmcnt(3)
	v_mfma_f32_16x16x32_bf16 v[22:25], v[242:245], v[130:133], v[22:25]
	v_mfma_f32_16x16x32_bf16 v[26:29], v[242:245], v[134:137], v[26:29]
	v_mfma_f32_16x16x32_bf16 v[30:33], v[242:245], v[138:141], v[30:33]
	v_mfma_f32_16x16x32_bf16 v[34:37], v[242:245], v[142:145], v[34:37]
	ds_read_b128 v[242:245], v233 offset:10240
	s_waitcnt lgkmcnt(3)
	v_mfma_f32_16x16x32_bf16 v[38:41], v[246:249], v[130:133], v[38:41]
	v_mfma_f32_16x16x32_bf16 v[42:45], v[246:249], v[134:137], v[42:45]
	v_mfma_f32_16x16x32_bf16 v[46:49], v[246:249], v[138:141], v[46:49]
	v_mfma_f32_16x16x32_bf16 v[50:53], v[246:249], v[142:145], v[50:53]
	ds_read_b128 v[246:249], v233 offset:12288
	s_waitcnt lgkmcnt(3)
	v_mfma_f32_16x16x32_bf16 v[54:57], v[250:253], v[130:133], v[54:57]
	v_mfma_f32_16x16x32_bf16 v[58:61], v[250:253], v[134:137], v[58:61]
	v_mfma_f32_16x16x32_bf16 v[62:65], v[250:253], v[138:141], v[62:65]
	v_mfma_f32_16x16x32_bf16 v[66:69], v[250:253], v[142:145], v[66:69]
	ds_read_b128 v[250:253], v233 offset:14336
	s_waitcnt lgkmcnt(3)
	v_mfma_f32_16x16x32_bf16 v[70:73], v[238:241], v[130:133], v[70:73]
	v_mfma_f32_16x16x32_bf16 v[74:77], v[238:241], v[134:137], v[74:77]
	v_mfma_f32_16x16x32_bf16 v[78:81], v[238:241], v[138:141], v[78:81]
	v_mfma_f32_16x16x32_bf16 v[82:85], v[238:241], v[142:145], v[82:85]
	s_waitcnt lgkmcnt(2)
	v_mfma_f32_16x16x32_bf16 v[86:89], v[242:245], v[130:133], v[86:89]
	v_mfma_f32_16x16x32_bf16 v[90:93], v[242:245], v[134:137], v[90:93]
	v_mfma_f32_16x16x32_bf16 v[94:97], v[242:245], v[138:141], v[94:97]
	v_mfma_f32_16x16x32_bf16 v[98:101], v[242:245], v[142:145], v[98:101]
	s_waitcnt lgkmcnt(0)
	s_waitcnt vmcnt(0)
	s_barrier
; #define GCOMPUTE(AS, BS) GCOMPUTE_KS(AS, BS, 0) GCOMPUTE_KS(AS, BS, 1)
; template <int EPI>
; DI void gemm_phase(const P& p, int l, const u16* __restrict__ A, const u16* __restrict__ Bt, int mpx, char* lds) {
;     ...
;   GCOMPUTE(As1, Bs1)
;   __builtin_amdgcn_sched_barrier(0);
;     ...
;     const int cb = n0 + wn * 64;
;     const bool isctx = m0 >= MLAT;
;     const int b = isctx ? ((m0 - MLAT) >> 8) : (m0 >> 11);
;     const int tokw = (isctx ? 2048 + ((m0 - MLAT) & 255) : (m0 & 2047)) + wm * 128;
;     u16* Tl = (u16*)(lds + 65536) + w * (64 * 72);
;     int kind = 0;
;     int tr = 0;
;     bool donorm = false;
;     if (cb >= 2816) { kind = 2; tr = 1; }
;     else if (cb < 256) tr = 1;
;     else if (cb < 512) tr = 0;
;     else if (cb < 1024) tr = 2;
;     else if (cb < 1408) { tr = 3; donorm = true; }
;     else if (cb < 1536) kind = 1;
;     else if (cb < 2048) tr = isctx ? 0 : 4;
;     else if (cb < 2304) kind = 1;
;     else if (cb < 2688) tr = isctx ? 0 : 3;
;     else kind = 1;
	v_mfma_f32_16x16x32_bf16 v[102:105], v[246:249], v[130:133], v[102:105]
	v_mfma_f32_16x16x32_bf16 v[106:109], v[246:249], v[134:137], v[106:109]
	v_mfma_f32_16x16x32_bf16 v[110:113], v[246:249], v[138:141], v[110:113]
	v_mfma_f32_16x16x32_bf16 v[114:117], v[246:249], v[142:145], v[114:117]
	v_mfma_f32_16x16x32_bf16 v[118:121], v[250:253], v[130:133], v[118:121]
	v_mfma_f32_16x16x32_bf16 v[122:125], v[250:253], v[134:137], v[122:125]
	v_mfma_f32_16x16x32_bf16 v[126:129], v[250:253], v[138:141], v[126:129]
	v_mfma_f32_16x16x32_bf16 v[2:5], v[250:253], v[142:145], v[2:5]
	s_nop 0
	v_readfirstlane_b32 s40, v195
	s_lshr_b32 s40, s40, 6
	s_and_b32 s41, s40, 3
	s_lshr_b32 s42, s40, 2
	s_lshr_b32 s43, s46, 6
	s_add_i32 s43, s43, s41
	s_cmp_ge_u32 s66, 0x8000
	s_cselect_b32 s67, 1, 0
	s_mov_b32 s44, 0xffff
	s_mov_b32 s45, 0
	s_bitcmp1_b64 s[44:45], s43
	s_cbranch_scc1 .Lfe_kind0
	s_mov_b32 s44, 0xc00000
	s_mov_b32 s45, 0xc0f
	s_bitcmp1_b64 s[44:45], s43
	s_cbranch_scc1 .Lfe_kind1
	s_cmp_ge_u32 s43, 44
	s_cbranch_scc1 .Lfe_kind2
	s_branch .Lfe_kind0
